# P0 sampled-absmax items: two rounds of lookahead (24 loads in flight before the first consume), counted vmcnt
# speedup vs baseline: 1.0023x; 1.0007x over previous
; __device__ __forceinline__ float p0_absmax_item(const float* W, int K, int N, int item, int lane, int nmin) {
;     (void)K; const int nblk = (N + 31) / 32, kb = item / nblk, nb = item % nblk, k0 = 64 * kb, n0 = 32 * nb;
;     const int nn = n0 + (lane & 31); const bool okr = nn < N && nn >= nmin;
;     float m = 0.f;
; #pragma unroll
;     for (int i = 0; i < 32; ++i) { const int kk = 2 * i + (lane >> 5); m = fmaxf(m, fabsf(okr ? W[(size_t)(k0 + kk) * N + nn] : 0.f)); }
;     return m;
.LBB0_57:
	v_lshlrev_b32_e32 v6, 2, v2
	v_lshl_add_u64 v[22:23], s[34:35], 0, v[6:7]
	s_waitcnt lgkmcnt(0)
	v_mov_b32_e32 v11, v7
	v_lshl_add_u64 v[22:23], v[22:23], 0, v[10:11]
	v_add_co_u32_e32 v24, vcc, 0x9000, v22
	s_nop 1
	v_addc_co_u32_e32 v25, vcc, 0, v23, vcc
	v_add_co_u32_e32 v26, vcc, 0x27000, v22
	s_nop 1
	v_addc_co_u32_e32 v27, vcc, 0, v23, vcc
	v_add_co_u32_e32 v28, vcc, 0x45000, v22
	s_nop 1
	v_addc_co_u32_e32 v29, vcc, 0, v23, vcc
	v_add_co_u32_e32 v98, vcc, 0x63000, v22
	s_nop 1
	v_addc_co_u32_e32 v99, vcc, 0, v23, vcc
	v_add_co_u32_e32 v100, vcc, 0x81000, v22
	s_nop 1
	v_addc_co_u32_e32 v101, vcc, 0, v23, vcc
	v_add_co_u32_e32 v102, vcc, 0x9f000, v22
	s_nop 1
	v_addc_co_u32_e32 v103, vcc, 0, v23, vcc
	v_add_co_u32_e32 v104, vcc, 0xbd000, v22
	s_nop 1
	v_addc_co_u32_e32 v105, vcc, 0, v23, vcc
	v_add_co_u32_e32 v106, vcc, 0xdb000, v22
	s_nop 1
	v_addc_co_u32_e32 v107, vcc, 0, v23, vcc
	global_load_dword v6, v[24:25], off offset:128
	global_load_dword v11, v[26:27], off offset:256
	global_load_dword v21, v[28:29], off offset:384
	global_load_dword v97, v[98:99], off offset:512
	global_load_dword v108, v[100:101], off offset:640
	global_load_dword v109, v[102:103], off offset:768
	global_load_dword v110, v[104:105], off offset:896
	global_load_dword v111, v[106:107], off offset:1024
	v_add_co_u32_e32 v24, vcc, 0xf9000, v22
	s_nop 1
	v_addc_co_u32_e32 v25, vcc, 0, v23, vcc
	v_add_co_u32_e32 v26, vcc, 0x117000, v22
	s_nop 1
	v_addc_co_u32_e32 v27, vcc, 0, v23, vcc
	v_add_co_u32_e32 v28, vcc, 0x135000, v22
	s_nop 1
	v_addc_co_u32_e32 v29, vcc, 0, v23, vcc
	v_add_co_u32_e32 v98, vcc, 0x153000, v22
	s_nop 1
	v_addc_co_u32_e32 v99, vcc, 0, v23, vcc
	v_add_co_u32_e32 v100, vcc, 0x171000, v22
	s_nop 1
	v_addc_co_u32_e32 v101, vcc, 0, v23, vcc
	v_add_co_u32_e32 v102, vcc, 0x18f000, v22
	s_nop 1
	v_addc_co_u32_e32 v103, vcc, 0, v23, vcc
	v_add_co_u32_e32 v104, vcc, 0x1ad000, v22
	s_nop 1
	v_addc_co_u32_e32 v105, vcc, 0, v23, vcc
	v_add_co_u32_e32 v106, vcc, 0x1cb000, v22
	s_nop 1
	v_addc_co_u32_e32 v107, vcc, 0, v23, vcc
	global_load_dword v112, v[24:25], off offset:1152
	global_load_dword v113, v[26:27], off offset:1280
	global_load_dword v114, v[28:29], off offset:1408
	global_load_dword v115, v[98:99], off offset:1536
	global_load_dword v116, v[100:101], off offset:1664
	global_load_dword v117, v[102:103], off offset:1792
	global_load_dword v118, v[104:105], off offset:1920
	global_load_dword v119, v[106:107], off offset:2048
	v_add_co_u32_e32 v24, vcc, 0x1e9000, v22
	s_nop 1
	v_addc_co_u32_e32 v25, vcc, 0, v23, vcc
	v_add_co_u32_e32 v26, vcc, 0x207000, v22
	s_nop 1
	v_addc_co_u32_e32 v27, vcc, 0, v23, vcc
	v_add_co_u32_e32 v28, vcc, 0x225000, v22
	s_nop 1
	v_addc_co_u32_e32 v29, vcc, 0, v23, vcc
	v_add_co_u32_e32 v98, vcc, 0x243000, v22
	s_nop 1
	v_addc_co_u32_e32 v99, vcc, 0, v23, vcc
	v_add_co_u32_e32 v100, vcc, 0x261000, v22
	s_nop 1
	v_addc_co_u32_e32 v101, vcc, 0, v23, vcc
	v_add_co_u32_e32 v102, vcc, 0x27f000, v22
	s_nop 1
	v_addc_co_u32_e32 v103, vcc, 0, v23, vcc
	v_add_co_u32_e32 v104, vcc, 0x29d000, v22
	s_nop 1
	v_addc_co_u32_e32 v105, vcc, 0, v23, vcc
	v_add_co_u32_e32 v106, vcc, 0x2bb000, v22
	s_nop 1
	v_addc_co_u32_e32 v107, vcc, 0, v23, vcc
	global_load_dword v120, v[24:25], off offset:2176
	global_load_dword v121, v[26:27], off offset:2304
	global_load_dword v122, v[28:29], off offset:2432
	global_load_dword v123, v[98:99], off offset:2560
	global_load_dword v124, v[100:101], off offset:2688
	global_load_dword v125, v[102:103], off offset:2816
	global_load_dword v126, v[104:105], off offset:2944
	s_nop 0
	global_load_dword v106, v[106:107], off offset:3072
	s_waitcnt vmcnt(22)
	v_max3_f32 v6, |v6|, 0, |v11|
	s_waitcnt vmcnt(20)
; __device__ __forceinline__ float p0_absmax_item(const float* W, int K, int N, int item, int lane, int nmin) {
;     (void)K; const int nblk = (N + 31) / 32, kb = item / nblk, nb = item % nblk, k0 = 64 * kb, n0 = 32 * nb;
;     const int nn = n0 + (lane & 31); const bool okr = nn < N && nn >= nmin;
;     float m = 0.f;
; #pragma unroll
;     for (int i = 0; i < 32; ++i) { const int kk = 2 * i + (lane >> 5); m = fmaxf(m, fabsf(okr ? W[(size_t)(k0 + kk) * N + nn] : 0.f)); }
;     return m;
	v_max3_f32 v6, v6, |v21|, |v97|
	s_waitcnt vmcnt(18)
	v_max3_f32 v6, v6, |v108|, |v109|
	s_waitcnt vmcnt(16)
	v_max3_f32 v6, v6, |v110|, |v111|
	v_add_co_u32_e32 v24, vcc, 0x2d9000, v22
	s_nop 1
	v_addc_co_u32_e32 v25, vcc, 0, v23, vcc
	v_add_co_u32_e32 v26, vcc, 0x2f7000, v22
	s_nop 1
	v_addc_co_u32_e32 v27, vcc, 0, v23, vcc
	v_add_co_u32_e32 v28, vcc, 0x315000, v22
	s_nop 1
	v_addc_co_u32_e32 v29, vcc, 0, v23, vcc
	v_add_co_u32_e32 v98, vcc, 0x333000, v22
	s_nop 1
	v_addc_co_u32_e32 v99, vcc, 0, v23, vcc
	v_add_co_u32_e32 v100, vcc, 0x351000, v22
	s_nop 1
	v_addc_co_u32_e32 v101, vcc, 0, v23, vcc
	v_add_co_u32_e32 v102, vcc, 0x36f000, v22
	s_nop 1
	v_addc_co_u32_e32 v103, vcc, 0, v23, vcc
	v_add_co_u32_e32 v104, vcc, 0x38d000, v22
	s_nop 1
	v_addc_co_u32_e32 v105, vcc, 0, v23, vcc
	v_add_co_u32_e32 v22, vcc, 0x3ac000, v22
	s_nop 1
	v_addc_co_u32_e32 v23, vcc, 0, v23, vcc
	global_load_dword v24, v[24:25], off offset:3200
	s_nop 0
	global_load_dword v25, v[26:27], off offset:3328
	s_nop 0
	global_load_dword v26, v[28:29], off offset:3456
	global_load_dword v27, v[98:99], off offset:3584
	s_nop 0
	global_load_dword v28, v[100:101], off offset:3712
	global_load_dword v29, v[102:103], off offset:3840
	global_load_dword v98, v[104:105], off offset:3968
	s_nop 0
	global_load_dword v22, v[22:23], off
	s_waitcnt vmcnt(22)
	v_max3_f32 v6, v6, |v112|, |v113|
	s_waitcnt vmcnt(20)
	v_max3_f32 v6, v6, |v114|, |v115|
	s_waitcnt vmcnt(18)
	v_max3_f32 v6, v6, |v116|, |v117|
	s_waitcnt vmcnt(16)
	v_max3_f32 v6, v6, |v118|, |v119|
	s_waitcnt vmcnt(14)
	v_max3_f32 v6, v6, |v120|, |v121|
	s_waitcnt vmcnt(12)
	v_max3_f32 v6, v6, |v122|, |v123|
	s_waitcnt vmcnt(10)
	v_max3_f32 v6, v6, |v124|, |v125|
	s_waitcnt vmcnt(8)
	v_max3_f32 v6, v6, |v126|, |v106|
	v_cmp_lt_i32_e32 vcc, v14, v16
	s_waitcnt vmcnt(6)
	v_max3_f32 v6, v6, |v24|, |v25|
	v_cndmask_b32_e32 v11, v93, v14, vcc
	s_waitcnt vmcnt(4)
	v_max3_f32 v6, v6, |v26|, |v27|
	v_lshlrev_b32_e32 v11, 2, v11
	s_waitcnt vmcnt(2)
	v_max3_f32 v6, v6, |v28|, |v29|
	v_cmp_lt_i32_e32 vcc, v15, v16
	s_waitcnt vmcnt(0)
	v_max3_f32 v6, v6, |v98|, |v22|
	ds_bpermute_b32 v11, v11, v6
	s_waitcnt lgkmcnt(0)
	v_max_f32_e32 v11, v11, v11
	v_max_f32_e32 v6, v6, v11
	v_cndmask_b32_e32 v11, v93, v15, vcc
	v_lshlrev_b32_e32 v11, 2, v11
	ds_bpermute_b32 v11, v11, v6
	v_cmp_lt_i32_e32 vcc, v17, v16
	s_waitcnt lgkmcnt(0)
	v_max_f32_e32 v11, v11, v11
	v_max_f32_e32 v6, v6, v11
	v_cndmask_b32_e32 v11, v93, v17, vcc
	v_lshlrev_b32_e32 v11, 2, v11
	ds_bpermute_b32 v11, v11, v6
	v_cmp_lt_i32_e32 vcc, v18, v16
	s_waitcnt lgkmcnt(0)
	v_max_f32_e32 v11, v11, v11
	v_max_f32_e32 v6, v6, v11
	v_cndmask_b32_e32 v11, v93, v18, vcc
	v_lshlrev_b32_e32 v11, 2, v11
	ds_bpermute_b32 v11, v11, v6
	v_cmp_lt_i32_e32 vcc, v19, v16
	s_waitcnt lgkmcnt(0)
	v_max_f32_e32 v11, v11, v11
	v_max_f32_e32 v6, v6, v11
	v_cndmask_b32_e32 v11, v93, v19, vcc
	v_lshlrev_b32_e32 v11, 2, v11
	ds_bpermute_b32 v11, v11, v6
	v_cmp_lt_i32_e32 vcc, v20, v16
	s_waitcnt lgkmcnt(0)
	v_max_f32_e32 v11, v11, v11
	v_max_f32_e32 v6, v6, v11
	v_cndmask_b32_e32 v11, v93, v20, vcc
	v_lshlrev_b32_e32 v11, 2, v11
	ds_bpermute_b32 v11, v11, v6
	s_waitcnt lgkmcnt(0)
	v_max_f32_e32 v11, v11, v11
	v_max_f32_e32 v14, v6, v11
	v_mul_f32_e32 v6, 0x41000000, v14
	v_max_f32_e32 v6, 0xda24260, v6
	v_div_scale_f32 v11, s[30:31], v6, v6, s47
	v_rcp_f32_e32 v15, v11
	s_nop 0
	v_fma_f32 v16, -v11, v15, 1.0
	v_fmac_f32_e32 v15, v16, v15
	v_div_scale_f32 v16, vcc, s47, v6, s47
	v_mul_f32_e32 v17, v16, v15
	v_fma_f32 v18, -v11, v17, v16
	v_fmac_f32_e32 v17, v18, v15
	v_fma_f32 v11, -v11, v17, v16
	v_div_fmas_f32 v11, v11, v15, v17
	s_and_saveexec_b64 s[30:31], s[38:39]
	s_cbranch_execz .LBB0_62
	s_mov_b64 s[36:37], exec
	s_mov_b32 s40, 0

; __device__ __forceinline__ float p0_absmax_item(const float* W, int K, int N, int item, int lane, int nmin) {
;     (void)K; const int nblk = (N + 31) / 32, kb = item / nblk, nb = item % nblk, k0 = 64 * kb, n0 = 32 * nb;
;     const int nn = n0 + (lane & 31); const bool okr = nn < N && nn >= nmin;
;     float m = 0.f;
; #pragma unroll
;     for (int i = 0; i < 32; ++i) { const int kk = 2 * i + (lane >> 5); m = fmaxf(m, fabsf(okr ? W[(size_t)(k0 + kk) * N + nn] : 0.f)); }
;     return m;
.LBB0_202:
	s_load_dwordx2 s[12:13], s[14:15], 0xe0
	s_lshl_b64 s[30:31], s[26:27], 2
	v_lshlrev_b32_e32 v6, 2, v2
	s_waitcnt lgkmcnt(0)
	s_add_u32 s12, s12, s30
	s_addc_u32 s13, s13, s31
	v_lshl_add_u64 v[20:21], s[12:13], 0, v[6:7]
	v_lshlrev_b32_e32 v6, 2, v12
	v_lshl_add_u64 v[20:21], v[20:21], 0, v[6:7]
	s_movk_i32 s12, 0x4000
	v_add_co_u32_e32 v22, vcc, 0x4000, v20
	s_nop 1
	v_addc_co_u32_e32 v23, vcc, 0, v21, vcc
	v_add_co_u32_e32 v24, vcc, 0x8000, v20
	s_nop 1
	v_addc_co_u32_e32 v25, vcc, 0, v21, vcc
	v_add_co_u32_e32 v26, vcc, 0xc000, v20
	s_nop 1
	v_addc_co_u32_e32 v27, vcc, 0, v21, vcc
	v_add_co_u32_e32 v28, vcc, 0x10000, v20
	s_nop 1
	v_addc_co_u32_e32 v29, vcc, 0, v21, vcc
	v_add_co_u32_e32 v98, vcc, 0x14000, v20
	s_nop 1
	v_addc_co_u32_e32 v99, vcc, 0, v21, vcc
	v_add_co_u32_e32 v100, vcc, 0x18000, v20
	s_nop 1
	v_addc_co_u32_e32 v101, vcc, 0, v21, vcc
	v_add_co_u32_e32 v102, vcc, 0x1c000, v20
	s_nop 1
	v_addc_co_u32_e32 v103, vcc, 0, v21, vcc
	global_load_dword v6, v[20:21], off
	global_load_dword v97, v[22:23], off
	global_load_dword v106, v[24:25], off
	global_load_dword v107, v[26:27], off
	global_load_dword v108, v[28:29], off
	global_load_dword v109, v[98:99], off
	global_load_dword v110, v[100:101], off
	global_load_dword v111, v[102:103], off
	v_add_co_u32_e32 v22, vcc, 0x20000, v20
	s_nop 1
	v_addc_co_u32_e32 v23, vcc, 0, v21, vcc
	v_add_co_u32_e32 v24, vcc, 0x24000, v20
	s_nop 1
	v_addc_co_u32_e32 v25, vcc, 0, v21, vcc
	v_add_co_u32_e32 v26, vcc, 0x28000, v20
	s_nop 1
	v_addc_co_u32_e32 v27, vcc, 0, v21, vcc
	v_add_co_u32_e32 v28, vcc, s60, v20
	s_nop 1
	v_addc_co_u32_e32 v29, vcc, 0, v21, vcc
	v_add_co_u32_e32 v98, vcc, 0x30000, v20
	s_nop 1
	v_addc_co_u32_e32 v99, vcc, 0, v21, vcc
	v_add_co_u32_e32 v100, vcc, 0x34000, v20
	s_nop 1
	v_addc_co_u32_e32 v101, vcc, 0, v21, vcc
	v_add_co_u32_e32 v102, vcc, s63, v20
	s_nop 1
	v_addc_co_u32_e32 v103, vcc, 0, v21, vcc
	v_add_co_u32_e32 v104, vcc, s64, v20
	s_nop 1
	v_addc_co_u32_e32 v105, vcc, 0, v21, vcc
	global_load_dword v112, v[22:23], off
	global_load_dword v113, v[24:25], off
	global_load_dword v114, v[26:27], off
	global_load_dword v115, v[28:29], off
	global_load_dword v116, v[98:99], off
	global_load_dword v117, v[100:101], off
	global_load_dword v118, v[102:103], off
	global_load_dword v119, v[104:105], off
	v_add_co_u32_e32 v22, vcc, s65, v20
	s_nop 1
	v_addc_co_u32_e32 v23, vcc, 0, v21, vcc
	v_add_co_u32_e32 v24, vcc, s66, v20
	s_nop 1
	v_addc_co_u32_e32 v25, vcc, 0, v21, vcc
	v_add_co_u32_e32 v26, vcc, s67, v20
	s_nop 1
	v_addc_co_u32_e32 v27, vcc, 0, v21, vcc
	v_add_co_u32_e32 v28, vcc, s68, v20
	s_nop 1
	v_addc_co_u32_e32 v29, vcc, 0, v21, vcc
	v_add_co_u32_e32 v98, vcc, s69, v20
	s_nop 1
	v_addc_co_u32_e32 v99, vcc, 0, v21, vcc
	v_add_co_u32_e32 v100, vcc, s72, v20
	s_nop 1
	v_addc_co_u32_e32 v101, vcc, 0, v21, vcc
	v_add_co_u32_e32 v102, vcc, s73, v20
	s_nop 1
	v_addc_co_u32_e32 v103, vcc, 0, v21, vcc
	v_add_co_u32_e32 v104, vcc, s74, v20
	s_nop 1
	v_addc_co_u32_e32 v105, vcc, 0, v21, vcc
	global_load_dword v120, v[22:23], off
	global_load_dword v121, v[24:25], off
	global_load_dword v122, v[26:27], off
	global_load_dword v123, v[28:29], off
	global_load_dword v124, v[98:99], off
	global_load_dword v125, v[100:101], off
	global_load_dword v126, v[102:103], off
	s_nop 0
	global_load_dword v104, v[104:105], off
	s_waitcnt vmcnt(22)
	v_max3_f32 v6, |v6|, 0, |v97|
	s_waitcnt vmcnt(20)
	v_max3_f32 v6, v6, |v106|, |v107|
	s_waitcnt vmcnt(18)
	v_max3_f32 v6, v6, |v108|, |v109|
	s_waitcnt vmcnt(16)
	v_max3_f32 v6, v6, |v110|, |v111|
	v_add_co_u32_e32 v22, vcc, s75, v20
	s_nop 1
	v_addc_co_u32_e32 v23, vcc, 0, v21, vcc
	v_add_co_u32_e32 v24, vcc, s76, v20
	s_nop 1
	v_addc_co_u32_e32 v25, vcc, 0, v21, vcc
	v_add_co_u32_e32 v26, vcc, s77, v20
	s_nop 1
	v_addc_co_u32_e32 v27, vcc, 0, v21, vcc
	v_add_co_u32_e32 v28, vcc, s78, v20
	s_nop 1
	v_addc_co_u32_e32 v29, vcc, 0, v21, vcc
	v_add_co_u32_e32 v98, vcc, s79, v20
	s_nop 1
	v_addc_co_u32_e32 v99, vcc, 0, v21, vcc
	v_add_co_u32_e32 v100, vcc, s80, v20
	s_nop 1
	v_addc_co_u32_e32 v101, vcc, 0, v21, vcc
	v_add_co_u32_e32 v102, vcc, s81, v20
	s_nop 1
	v_addc_co_u32_e32 v103, vcc, 0, v21, vcc
	v_add_co_u32_e32 v20, vcc, s82, v20
	s_nop 1
	v_addc_co_u32_e32 v21, vcc, 0, v21, vcc
	global_load_dword v22, v[22:23], off
	s_nop 0
	global_load_dword v23, v[24:25], off
	s_nop 0
	global_load_dword v24, v[26:27], off
	global_load_dword v25, v[28:29], off
	s_nop 0
	global_load_dword v26, v[98:99], off
	global_load_dword v27, v[100:101], off
	global_load_dword v28, v[102:103], off
	s_nop 0
	global_load_dword v20, v[20:21], off
	s_waitcnt vmcnt(22)
	v_max3_f32 v6, v6, |v112|, |v113|
	s_waitcnt vmcnt(20)
	v_max3_f32 v6, v6, |v114|, |v115|
	s_waitcnt vmcnt(18)
	v_max3_f32 v6, v6, |v116|, |v117|
	s_waitcnt vmcnt(16)
	v_max3_f32 v6, v6, |v118|, |v119|
	s_waitcnt vmcnt(14)
	v_max3_f32 v6, v6, |v120|, |v121|
	s_waitcnt vmcnt(12)
	v_max3_f32 v6, v6, |v122|, |v123|
	s_waitcnt vmcnt(10)
	v_max3_f32 v6, v6, |v124|, |v125|
	s_waitcnt vmcnt(8)
	v_max3_f32 v6, v6, |v126|, |v104|
	s_mov_b32 s12, 0x34000
	v_cmp_lt_i32_e32 vcc, v19, v11
	s_waitcnt vmcnt(6)
	v_max3_f32 v6, v6, |v22|, |v23|
	v_cndmask_b32_e32 v19, v93, v19, vcc
	s_waitcnt vmcnt(4)
	v_max3_f32 v6, v6, |v24|, |v25|
	v_lshlrev_b32_e32 v19, 2, v19
	s_waitcnt vmcnt(2)
	v_max3_f32 v6, v6, |v26|, |v27|
	v_cmp_lt_i32_e32 vcc, v18, v11
	s_waitcnt vmcnt(0)
	v_max3_f32 v6, v6, |v28|, |v20|
	ds_bpermute_b32 v19, v19, v6
	v_cndmask_b32_e32 v18, v93, v18, vcc
	v_lshlrev_b32_e32 v18, 2, v18
	v_cmp_lt_i32_e32 vcc, v17, v11
	s_waitcnt lgkmcnt(0)
	v_max_f32_e32 v19, v19, v19
	v_max_f32_e32 v6, v6, v19
	ds_bpermute_b32 v18, v18, v6
	v_cndmask_b32_e32 v17, v93, v17, vcc
	v_lshlrev_b32_e32 v17, 2, v17
	v_cmp_lt_i32_e32 vcc, v16, v11
	s_waitcnt lgkmcnt(0)
	v_max_f32_e32 v18, v18, v18
	v_max_f32_e32 v6, v6, v18
	ds_bpermute_b32 v17, v17, v6
	v_cndmask_b32_e32 v16, v93, v16, vcc
	v_lshlrev_b32_e32 v16, 2, v16
	v_cmp_lt_i32_e32 vcc, v15, v11
	s_waitcnt lgkmcnt(0)
	v_max_f32_e32 v17, v17, v17
	v_max_f32_e32 v6, v6, v17
	ds_bpermute_b32 v16, v16, v6
	v_cndmask_b32_e32 v15, v93, v15, vcc
	v_lshlrev_b32_e32 v15, 2, v15
	v_cmp_lt_i32_e32 vcc, v14, v11
	s_waitcnt lgkmcnt(0)
	v_max_f32_e32 v16, v16, v16
	v_max_f32_e32 v6, v6, v16
	ds_bpermute_b32 v15, v15, v6
	v_cndmask_b32_e32 v11, v93, v14, vcc
	v_lshlrev_b32_e32 v11, 2, v11
	s_waitcnt lgkmcnt(0)
	v_max_f32_e32 v15, v15, v15
	v_max_f32_e32 v6, v6, v15
	ds_bpermute_b32 v11, v11, v6
	s_waitcnt lgkmcnt(0)
	v_max_f32_e32 v11, v11, v11
	v_max_f32_e32 v14, v6, v11
	v_mul_f32_e32 v6, 0x41000000, v14
	v_max_f32_e32 v6, 0xda24260, v6
	v_div_scale_f32 v11, s[12:13], v6, v6, s47
	v_rcp_f32_e32 v15, v11
	s_nop 0
	v_fma_f32 v16, -v11, v15, 1.0
	v_fmac_f32_e32 v15, v16, v15
	v_div_scale_f32 v16, vcc, s47, v6, s47
	v_mul_f32_e32 v17, v16, v15
	v_fma_f32 v18, -v11, v17, v16
	v_fmac_f32_e32 v17, v18, v15
	v_fma_f32 v11, -v11, v17, v16
	v_div_fmas_f32 v11, v11, v15, v17
	s_and_saveexec_b64 s[30:31], s[38:39]
	s_cbranch_execz .LBB0_207
	s_mov_b64 s[36:37], exec
	s_mov_b32 s12, 0

; __device__ __forceinline__ float p0_absmax_item(const float* W, int K, int N, int item, int lane, int nmin) {
;     (void)K; const int nblk = (N + 31) / 32, kb = item / nblk, nb = item % nblk, k0 = 64 * kb, n0 = 32 * nb;
;     const int nn = n0 + (lane & 31); const bool okr = nn < N && nn >= nmin;
;     float m = 0.f;
; #pragma unroll
;     for (int i = 0; i < 32; ++i) { const int kk = 2 * i + (lane >> 5); m = fmaxf(m, fabsf(okr ? W[(size_t)(k0 + kk) * N + nn] : 0.f)); }
;     return m;
.LBB0_279:
	s_load_dwordx2 s[12:13], s[14:15], 0x20
	s_lshl_b64 s[30:31], s[26:27], 2
	v_lshlrev_b32_e32 v6, 2, v2
	s_waitcnt lgkmcnt(0)
	s_add_u32 s12, s12, s30
	s_addc_u32 s13, s13, s31
	v_lshl_add_u64 v[20:21], s[12:13], 0, v[6:7]
	v_lshlrev_b32_e32 v6, 2, v12
	v_lshl_add_u64 v[20:21], v[20:21], 0, v[6:7]
	s_movk_i32 s12, 0x4000
	v_add_co_u32_e32 v22, vcc, 0x4000, v20
	s_nop 1
	v_addc_co_u32_e32 v23, vcc, 0, v21, vcc
	v_add_co_u32_e32 v24, vcc, 0x8000, v20
	s_nop 1
	v_addc_co_u32_e32 v25, vcc, 0, v21, vcc
	v_add_co_u32_e32 v26, vcc, 0xc000, v20
	s_nop 1
	v_addc_co_u32_e32 v27, vcc, 0, v21, vcc
	v_add_co_u32_e32 v28, vcc, 0x10000, v20
	s_nop 1
	v_addc_co_u32_e32 v29, vcc, 0, v21, vcc
	v_add_co_u32_e32 v98, vcc, 0x14000, v20
	s_nop 1
	v_addc_co_u32_e32 v99, vcc, 0, v21, vcc
	v_add_co_u32_e32 v100, vcc, 0x18000, v20
	s_nop 1
	v_addc_co_u32_e32 v101, vcc, 0, v21, vcc
	v_add_co_u32_e32 v102, vcc, 0x1c000, v20
	s_nop 1
	v_addc_co_u32_e32 v103, vcc, 0, v21, vcc
	global_load_dword v6, v[20:21], off
	global_load_dword v97, v[22:23], off
	global_load_dword v106, v[24:25], off
	global_load_dword v107, v[26:27], off
	global_load_dword v108, v[28:29], off
	global_load_dword v109, v[98:99], off
	global_load_dword v110, v[100:101], off
	global_load_dword v111, v[102:103], off
	v_add_co_u32_e32 v22, vcc, 0x20000, v20
	s_nop 1
	v_addc_co_u32_e32 v23, vcc, 0, v21, vcc
	v_add_co_u32_e32 v24, vcc, 0x24000, v20
	s_nop 1
	v_addc_co_u32_e32 v25, vcc, 0, v21, vcc
	v_add_co_u32_e32 v26, vcc, 0x28000, v20
	s_nop 1
	v_addc_co_u32_e32 v27, vcc, 0, v21, vcc
	v_add_co_u32_e32 v28, vcc, s60, v20
	s_nop 1
	v_addc_co_u32_e32 v29, vcc, 0, v21, vcc
	v_add_co_u32_e32 v98, vcc, 0x30000, v20
	s_nop 1
	v_addc_co_u32_e32 v99, vcc, 0, v21, vcc
	v_add_co_u32_e32 v100, vcc, 0x34000, v20
	s_nop 1
	v_addc_co_u32_e32 v101, vcc, 0, v21, vcc
	v_add_co_u32_e32 v102, vcc, s63, v20
	s_nop 1
	v_addc_co_u32_e32 v103, vcc, 0, v21, vcc
	v_add_co_u32_e32 v104, vcc, s64, v20
	s_nop 1
	v_addc_co_u32_e32 v105, vcc, 0, v21, vcc
	global_load_dword v112, v[22:23], off
	global_load_dword v113, v[24:25], off
	global_load_dword v114, v[26:27], off
	global_load_dword v115, v[28:29], off
	global_load_dword v116, v[98:99], off
	global_load_dword v117, v[100:101], off
	global_load_dword v118, v[102:103], off
	global_load_dword v119, v[104:105], off
	v_add_co_u32_e32 v22, vcc, s65, v20
	s_nop 1
	v_addc_co_u32_e32 v23, vcc, 0, v21, vcc
	v_add_co_u32_e32 v24, vcc, s66, v20
	s_nop 1
	v_addc_co_u32_e32 v25, vcc, 0, v21, vcc
	v_add_co_u32_e32 v26, vcc, s67, v20
	s_nop 1
	v_addc_co_u32_e32 v27, vcc, 0, v21, vcc
	v_add_co_u32_e32 v28, vcc, s68, v20
	s_nop 1
	v_addc_co_u32_e32 v29, vcc, 0, v21, vcc
	v_add_co_u32_e32 v98, vcc, s69, v20
	s_nop 1
	v_addc_co_u32_e32 v99, vcc, 0, v21, vcc
	v_add_co_u32_e32 v100, vcc, s72, v20
	s_nop 1
	v_addc_co_u32_e32 v101, vcc, 0, v21, vcc
	v_add_co_u32_e32 v102, vcc, s73, v20
	s_nop 1
	v_addc_co_u32_e32 v103, vcc, 0, v21, vcc
	v_add_co_u32_e32 v104, vcc, s74, v20
	s_nop 1
	v_addc_co_u32_e32 v105, vcc, 0, v21, vcc
	global_load_dword v120, v[22:23], off
	global_load_dword v121, v[24:25], off
	global_load_dword v122, v[26:27], off
	global_load_dword v123, v[28:29], off
	global_load_dword v124, v[98:99], off
	global_load_dword v125, v[100:101], off
	global_load_dword v126, v[102:103], off
	s_nop 0
	global_load_dword v104, v[104:105], off
	s_waitcnt vmcnt(22)
	v_max3_f32 v6, |v6|, 0, |v97|
	s_waitcnt vmcnt(20)
	v_max3_f32 v6, v6, |v106|, |v107|
	s_waitcnt vmcnt(18)
	v_max3_f32 v6, v6, |v108|, |v109|
	s_waitcnt vmcnt(16)
	v_max3_f32 v6, v6, |v110|, |v111|
	v_add_co_u32_e32 v22, vcc, s75, v20
	s_nop 1
	v_addc_co_u32_e32 v23, vcc, 0, v21, vcc
	v_add_co_u32_e32 v24, vcc, s76, v20
	s_nop 1
	v_addc_co_u32_e32 v25, vcc, 0, v21, vcc
	v_add_co_u32_e32 v26, vcc, s77, v20
	s_nop 1
	v_addc_co_u32_e32 v27, vcc, 0, v21, vcc
	v_add_co_u32_e32 v28, vcc, s78, v20
	s_nop 1
	v_addc_co_u32_e32 v29, vcc, 0, v21, vcc
	v_add_co_u32_e32 v98, vcc, s79, v20
	s_nop 1
	v_addc_co_u32_e32 v99, vcc, 0, v21, vcc
	v_add_co_u32_e32 v100, vcc, s80, v20
	s_nop 1
	v_addc_co_u32_e32 v101, vcc, 0, v21, vcc
	v_add_co_u32_e32 v102, vcc, s81, v20
	s_nop 1
	v_addc_co_u32_e32 v103, vcc, 0, v21, vcc
	v_add_co_u32_e32 v20, vcc, s82, v20
	s_nop 1
	v_addc_co_u32_e32 v21, vcc, 0, v21, vcc
	global_load_dword v22, v[22:23], off
	s_nop 0
	global_load_dword v23, v[24:25], off
	s_nop 0
	global_load_dword v24, v[26:27], off
	global_load_dword v25, v[28:29], off
	s_nop 0
	global_load_dword v26, v[98:99], off
	global_load_dword v27, v[100:101], off
	global_load_dword v28, v[102:103], off
	s_nop 0
	global_load_dword v20, v[20:21], off
	s_waitcnt vmcnt(22)
	v_max3_f32 v6, v6, |v112|, |v113|
	s_waitcnt vmcnt(20)
	v_max3_f32 v6, v6, |v114|, |v115|
	s_waitcnt vmcnt(18)
	v_max3_f32 v6, v6, |v116|, |v117|
	s_waitcnt vmcnt(16)
	v_max3_f32 v6, v6, |v118|, |v119|
	s_waitcnt vmcnt(14)
	v_max3_f32 v6, v6, |v120|, |v121|
	s_waitcnt vmcnt(12)
	v_max3_f32 v6, v6, |v122|, |v123|
	s_waitcnt vmcnt(10)
	v_max3_f32 v6, v6, |v124|, |v125|
	s_waitcnt vmcnt(8)
	v_max3_f32 v6, v6, |v126|, |v104|
	s_mov_b32 s12, 0x34000
	v_cmp_lt_i32_e32 vcc, v11, v15
	s_waitcnt vmcnt(6)
	v_max3_f32 v6, v6, |v22|, |v23|
	v_cndmask_b32_e32 v11, v93, v11, vcc
	s_waitcnt vmcnt(4)
	v_max3_f32 v6, v6, |v24|, |v25|
	v_lshlrev_b32_e32 v11, 2, v11
	s_waitcnt vmcnt(2)
	v_max3_f32 v6, v6, |v26|, |v27|
	v_cmp_lt_i32_e32 vcc, v14, v15
	s_waitcnt vmcnt(0)
	v_max3_f32 v6, v6, |v28|, |v20|
	ds_bpermute_b32 v11, v11, v6
	s_waitcnt lgkmcnt(0)
	v_max_f32_e32 v11, v11, v11
	v_max_f32_e32 v6, v6, v11
	v_cndmask_b32_e32 v11, v93, v14, vcc
	v_lshlrev_b32_e32 v11, 2, v11
	ds_bpermute_b32 v11, v11, v6
	v_cmp_lt_i32_e32 vcc, v16, v15
	s_waitcnt lgkmcnt(0)
	v_max_f32_e32 v11, v11, v11
	v_max_f32_e32 v6, v6, v11
	v_cndmask_b32_e32 v11, v93, v16, vcc
	v_lshlrev_b32_e32 v11, 2, v11
	ds_bpermute_b32 v11, v11, v6
	v_cmp_lt_i32_e32 vcc, v17, v15
	s_waitcnt lgkmcnt(0)
	v_max_f32_e32 v11, v11, v11
	v_max_f32_e32 v6, v6, v11
	v_cndmask_b32_e32 v11, v93, v17, vcc
	v_lshlrev_b32_e32 v11, 2, v11
	ds_bpermute_b32 v11, v11, v6
	v_cmp_lt_i32_e32 vcc, v18, v15
	s_waitcnt lgkmcnt(0)
	v_max_f32_e32 v11, v11, v11
	v_max_f32_e32 v6, v6, v11
	v_cndmask_b32_e32 v11, v93, v18, vcc
	v_lshlrev_b32_e32 v11, 2, v11
	ds_bpermute_b32 v11, v11, v6
	v_cmp_lt_i32_e32 vcc, v19, v15
	s_waitcnt lgkmcnt(0)
	v_max_f32_e32 v11, v11, v11
	v_max_f32_e32 v6, v6, v11
	v_cndmask_b32_e32 v11, v93, v19, vcc
	v_lshlrev_b32_e32 v11, 2, v11
	ds_bpermute_b32 v11, v11, v6
	s_waitcnt lgkmcnt(0)
	v_max_f32_e32 v11, v11, v11
	v_max_f32_e32 v14, v6, v11
	v_mul_f32_e32 v6, 0x41000000, v14
	v_max_f32_e32 v6, 0xda24260, v6
	v_div_scale_f32 v11, s[12:13], v6, v6, s47
	v_rcp_f32_e32 v15, v11
	s_nop 0
	v_fma_f32 v16, -v11, v15, 1.0
	v_fmac_f32_e32 v15, v16, v15
	v_div_scale_f32 v16, vcc, s47, v6, s47
	v_mul_f32_e32 v17, v16, v15
	v_fma_f32 v18, -v11, v17, v16
	v_fmac_f32_e32 v17, v18, v15
	v_fma_f32 v11, -v11, v17, v16
	v_div_fmas_f32 v11, v11, v15, v17
	s_and_saveexec_b64 s[30:31], s[38:39]
	s_cbranch_execz .LBB0_284
	s_mov_b64 s[36:37], exec
	s_mov_b32 s12, 0
